# bh2 + grid barrier release read off the cross-XCD arrival counter (no separate generation word hop)
# speedup vs baseline: 1.0058x; 1.0058x over previous
; __device__ __forceinline__ unsigned xb_ld(unsigned* p)              { return __hip_atomic_load(p, __ATOMIC_RELAXED, __HIP_MEMORY_SCOPE_AGENT); }
; __device__ __forceinline__ unsigned xb_add(unsigned* p, unsigned v) { return __hip_atomic_fetch_add(p, v, __ATOMIC_RELAXED, __HIP_MEMORY_SCOPE_AGENT); }
; #define XB_SPIN(cond, bar) do { unsigned _sp = 0; while (cond) { __builtin_amdgcn_s_sleep(1); \
;     if ((++_sp & 255u) == 0u) { if (xb_ld(&(bar)[XB_TMO])) break; if (_sp > XB_SPIN_CAP) { atomicAdd(&(bar)[XB_TMO], 1u); break; } } } } while (0)
; __device__ __forceinline__ void xcd_barrier(const XcdBarrier& b, int tid) {
;     ...
;         const unsigned old = xb_add(&bar[XB_XSUB(b.x)], 1u);
;         const unsigned gen = old / nloc;
;         if (old + 1u == (gen + 1u) * nloc) {
;             __builtin_amdgcn_fence(__ATOMIC_RELEASE, "agent");
;             asm volatile("s_waitcnt vmcnt(0)" ::: "memory");
;             const unsigned og = xb_add(&bar[XB_TOP], 1u);
;             const unsigned tg = og / nx;
;             if (og + 1u == (tg + 1u) * nx) xb_add(&bar[XB_TOPGEN], 1u);
;             else XB_SPIN(xb_ld(&bar[XB_TOPGEN]) == tg, bar);
;             __builtin_amdgcn_fence(__ATOMIC_ACQUIRE, "agent");
;             xb_add(&bar[XB_XGEN(b.x)], 1u);
;             asm volatile("s_waitcnt vmcnt(0)" ::: "memory");
;         } else {
;             XB_SPIN(xb_ld(&bar[XB_XGEN(b.x)]) == gen, bar);
.LBB0_105:
	s_or_b64 exec, exec, s[12:13]
	v_cvt_f32_u32_e32 v5, v3
	s_waitcnt vmcnt(0)
	buffer_inv sc1
	v_readfirstlane_b32 s3, v4
	v_sub_u32_e32 v4, 0, v3
	v_rcp_iflag_f32_e32 v5, v5
	v_add_u32_e32 v6, s3, v2
	v_mul_f32_e32 v5, 0x4f7ffffe, v5
	v_cvt_u32_f32_e32 v5, v5
	v_mul_lo_u32 v2, v4, v5
	v_mul_hi_u32 v2, v5, v2
	v_add_u32_e32 v2, v5, v2
	v_mul_hi_u32 v2, v6, v2
	v_mul_lo_u32 v4, v2, v3
	v_sub_u32_e32 v4, v6, v4
	v_add_u32_e32 v5, 1, v2
	v_cmp_ge_u32_e32 vcc, v4, v3
	s_nop 1
	v_cndmask_b32_e32 v2, v2, v5, vcc
	v_sub_u32_e32 v5, v4, v3
	v_cndmask_b32_e32 v4, v4, v5, vcc
	v_add_u32_e32 v5, 1, v2
	v_cmp_ge_u32_e32 vcc, v4, v3
	v_add_u32_e32 v4, 1, v6
	s_nop 0
	v_cndmask_b32_e32 v2, v2, v5, vcc
	v_mul_lo_u32 v5, v3, v2
	v_add_u32_e32 v3, v5, v3
	v_cmp_ne_u32_e32 vcc, v4, v3
	s_and_saveexec_b64 s[10:11], vcc
	s_xor_b64 s[10:11], exec, s[10:11]
	s_cbranch_execz .LBB0_119
	s_waitcnt lgkmcnt(0)
	v_add_u32_e32 v7, 1, v2
	v_mul_lo_u32 v7, v7, v1
	v_mov_b32_e32 v1, 0x3000
	global_load_dword v1, v1, s[6:7] offset:1024 sc1
	s_add_u32 s14, s6, 0x3400
	s_addc_u32 s15, s7, 0
	s_waitcnt vmcnt(0)
	v_cmp_lt_u32_e32 vcc, v1, v7
	s_and_saveexec_b64 s[12:13], vcc
	s_cbranch_execz .LBB0_118
	s_mov_b32 s3, 1
	s_mov_b64 s[16:17], 0
	v_mov_b32_e32 v1, 0
	s_branch .LBB0_109

; __device__ __forceinline__ unsigned xb_ld(unsigned* p)              { return __hip_atomic_load(p, __ATOMIC_RELAXED, __HIP_MEMORY_SCOPE_AGENT); }
; #define XB_SPIN(cond, bar) do { unsigned _sp = 0; while (cond) { __builtin_amdgcn_s_sleep(1); \
;     if ((++_sp & 255u) == 0u) { if (xb_ld(&(bar)[XB_TMO])) break; if (_sp > XB_SPIN_CAP) { atomicAdd(&(bar)[XB_TMO], 1u); break; } } } } while (0)
; __device__ __forceinline__ void xcd_barrier(const XcdBarrier& b, int tid) {
;     ...
;             XB_SPIN(xb_ld(&bar[XB_XGEN(b.x)]) == gen, bar);
.LBB0_111:
	global_load_dword v3, v1, s[14:15] sc1
	s_add_i32 s3, s3, 1
	s_mov_b64 s[22:23], -1
	s_waitcnt vmcnt(0)
	v_cmp_ge_u32_e32 vcc, v3, v7
	s_orn2_b64 s[20:21], vcc, exec
	s_branch .LBB0_108

; __device__ __forceinline__ unsigned xb_ld(unsigned* p)              { return __hip_atomic_load(p, __ATOMIC_RELAXED, __HIP_MEMORY_SCOPE_AGENT); }
; __device__ __forceinline__ unsigned xb_add(unsigned* p, unsigned v) { return __hip_atomic_fetch_add(p, v, __ATOMIC_RELAXED, __HIP_MEMORY_SCOPE_AGENT); }
; #define XB_SPIN(cond, bar) do { unsigned _sp = 0; while (cond) { __builtin_amdgcn_s_sleep(1); \
;     if ((++_sp & 255u) == 0u) { if (xb_ld(&(bar)[XB_TMO])) break; if (_sp > XB_SPIN_CAP) { atomicAdd(&(bar)[XB_TMO], 1u); break; } } } } while (0)
; __device__ __forceinline__ void xcd_barrier(const XcdBarrier& b, int tid) {
;     ...
;         if (old + 1u == (gen + 1u) * nloc) {
;             __builtin_amdgcn_fence(__ATOMIC_RELEASE, "agent");
;             asm volatile("s_waitcnt vmcnt(0)" ::: "memory");
;             const unsigned og = xb_add(&bar[XB_TOP], 1u);
;             const unsigned tg = og / nx;
;             if (og + 1u == (tg + 1u) * nx) xb_add(&bar[XB_TOPGEN], 1u);
;             else XB_SPIN(xb_ld(&bar[XB_TOPGEN]) == tg, bar);
.LBB0_122:
	s_or_b64 exec, exec, s[12:13]
	v_cvt_f32_u32_e32 v4, v1
	s_waitcnt vmcnt(0)
	v_readfirstlane_b32 s3, v3
	s_add_u32 s12, s6, 0x3400
	s_addc_u32 s13, s7, 0
	v_rcp_iflag_f32_e32 v4, v4
	v_add_u32_e32 v2, s3, v2
	v_add_u32_e32 v5, 1, v2
	s_mov_b64 s[14:15], -1
	v_mul_f32_e32 v3, 0x4f7ffffe, v4
	v_cvt_u32_f32_e32 v3, v3
	v_sub_u32_e32 v4, 0, v1
	v_mul_lo_u32 v4, v4, v3
	v_mul_hi_u32 v4, v3, v4
	v_add_u32_e32 v3, v3, v4
	v_mul_hi_u32 v3, v2, v3
	v_mul_lo_u32 v4, v3, v1
	v_sub_u32_e32 v2, v2, v4
	v_add_u32_e32 v6, 1, v3
	v_cmp_ge_u32_e32 vcc, v2, v1
	v_sub_u32_e32 v4, v2, v1
	s_nop 0
	v_cndmask_b32_e32 v3, v3, v6, vcc
	v_cndmask_b32_e32 v2, v2, v4, vcc
	v_add_u32_e32 v4, 1, v3
	v_cmp_ge_u32_e32 vcc, v2, v1
	s_nop 1
	v_cndmask_b32_e32 v4, v3, v4, vcc
	v_mul_lo_u32 v2, v1, v4
	v_add_u32_e32 v1, v2, v1
	v_mov_b32_e32 v7, v1
	v_cmp_ne_u32_e32 vcc, v5, v1
	v_mov_b64_e32 v[2:3], s[12:13]
	s_and_saveexec_b64 s[10:11], vcc
	s_cbranch_execz .LBB0_134
	v_mov_b32_e32 v1, 0
	global_load_dword v2, v1, s[12:13] sc1
	s_mov_b64 s[18:19], 0
	s_waitcnt vmcnt(0)
	v_cmp_lt_u32_e32 vcc, v2, v7
	s_and_saveexec_b64 s[16:17], vcc
	s_cbranch_execz .LBB0_133
	s_add_u32 s14, s6, 0x200
	s_addc_u32 s15, s7, 0
	s_mov_b32 s3, 1
	s_mov_b64 s[6:7], 0
	s_branch .LBB0_126

; __device__ __forceinline__ unsigned xb_ld(unsigned* p)              { return __hip_atomic_load(p, __ATOMIC_RELAXED, __HIP_MEMORY_SCOPE_AGENT); }
; #define XB_SPIN(cond, bar) do { unsigned _sp = 0; while (cond) { __builtin_amdgcn_s_sleep(1); \
;     if ((++_sp & 255u) == 0u) { if (xb_ld(&(bar)[XB_TMO])) break; if (_sp > XB_SPIN_CAP) { atomicAdd(&(bar)[XB_TMO], 1u); break; } } } } while (0)
; __device__ __forceinline__ void xcd_barrier(const XcdBarrier& b, int tid) {
;     ...
;             else XB_SPIN(xb_ld(&bar[XB_TOPGEN]) == tg, bar);
.LBB0_128:
	global_load_dword v2, v1, s[12:13] sc1
	s_add_i32 s3, s3, 1
	s_mov_b64 s[20:21], -1
	s_waitcnt vmcnt(0)
	v_cmp_ge_u32_e32 vcc, v2, v7
	s_orn2_b64 s[24:25], vcc, exec
	s_branch .LBB0_125

; __device__ __forceinline__ unsigned xb_ld(unsigned* p)              { return __hip_atomic_load(p, __ATOMIC_RELAXED, __HIP_MEMORY_SCOPE_AGENT); }
; __device__ __forceinline__ unsigned xb_add(unsigned* p, unsigned v) { return __hip_atomic_fetch_add(p, v, __ATOMIC_RELAXED, __HIP_MEMORY_SCOPE_AGENT); }
; #define XB_SPIN(cond, bar) do { unsigned _sp = 0; while (cond) { __builtin_amdgcn_s_sleep(1); \
;     if ((++_sp & 255u) == 0u) { if (xb_ld(&(bar)[XB_TMO])) break; if (_sp > XB_SPIN_CAP) { atomicAdd(&(bar)[XB_TMO], 1u); break; } } } } while (0)
; __device__ __forceinline__ void xcd_barrier(const XcdBarrier& b, int tid) {
;     ...
;             if (og + 1u == (tg + 1u) * nx) xb_add(&bar[XB_TOPGEN], 1u);
;             else XB_SPIN(xb_ld(&bar[XB_TOPGEN]) == tg, bar);
;             __builtin_amdgcn_fence(__ATOMIC_ACQUIRE, "agent");
;             xb_add(&bar[XB_XGEN(b.x)], 1u);
;             asm volatile("s_waitcnt vmcnt(0)" ::: "memory");
.LBB0_134:
	s_or_b64 exec, exec, s[10:11]
	s_and_saveexec_b64 s[6:7], s[14:15]
	s_cbranch_execz .LBB0_136
	v_mov_b32_e32 v1, 1
.LBB0_136:
	s_or_b64 exec, exec, s[6:7]
	s_mov_b64 s[6:7], exec
	v_mbcnt_lo_u32_b32 v1, s6, 0
	v_mbcnt_hi_u32_b32 v1, s7, v1
	v_cmp_eq_u32_e32 vcc, 0, v1
	s_waitcnt vmcnt(0)
	s_and_saveexec_b64 s[10:11], vcc
	s_cbranch_execz .LBB0_138
	s_bcnt1_i32_b64 s3, s[6:7]
	v_mov_b32_e32 v1, 0x2000
	v_mov_b32_e32 v2, s3

; __device__ __forceinline__ unsigned xb_ld(unsigned* p)              { return __hip_atomic_load(p, __ATOMIC_RELAXED, __HIP_MEMORY_SCOPE_AGENT); }
; __device__ __forceinline__ unsigned xb_add(unsigned* p, unsigned v) { return __hip_atomic_fetch_add(p, v, __ATOMIC_RELAXED, __HIP_MEMORY_SCOPE_AGENT); }
; #define XB_SPIN(cond, bar) do { unsigned _sp = 0; while (cond) { __builtin_amdgcn_s_sleep(1); \
;     if ((++_sp & 255u) == 0u) { if (xb_ld(&(bar)[XB_TMO])) break; if (_sp > XB_SPIN_CAP) { atomicAdd(&(bar)[XB_TMO], 1u); break; } } } } while (0)
; __device__ __forceinline__ void xcd_barrier(const XcdBarrier& b, int tid) {
;     ...
;             if (og + 1u == (tg + 1u) * nx) xb_add(&bar[XB_TOPGEN], 1u);
;             else XB_SPIN(xb_ld(&bar[XB_TOPGEN]) == tg, bar);
;             __builtin_amdgcn_fence(__ATOMIC_ACQUIRE, "agent");
;             xb_add(&bar[XB_XGEN(b.x)], 1u);
;             asm volatile("s_waitcnt vmcnt(0)" ::: "memory");
.LBB0_195:
	s_or_b64 exec, exec, s[10:11]
	s_and_saveexec_b64 s[6:7], s[14:15]
	s_cbranch_execz .LBB0_197
	v_mov_b32_e32 v1, 1
.LBB0_197:
	s_or_b64 exec, exec, s[6:7]
	s_mov_b64 s[6:7], exec
	v_mbcnt_lo_u32_b32 v1, s6, 0
	v_mbcnt_hi_u32_b32 v1, s7, v1
	v_cmp_eq_u32_e32 vcc, 0, v1
	s_waitcnt vmcnt(0)
	s_and_saveexec_b64 s[10:11], vcc
	s_cbranch_execz .LBB0_199
	s_bcnt1_i32_b64 s3, s[6:7]
	v_mov_b32_e32 v1, 0x2000
	v_mov_b32_e32 v2, s3

; __device__ __forceinline__ unsigned xb_ld(unsigned* p)              { return __hip_atomic_load(p, __ATOMIC_RELAXED, __HIP_MEMORY_SCOPE_AGENT); }
; __device__ __forceinline__ unsigned xb_add(unsigned* p, unsigned v) { return __hip_atomic_fetch_add(p, v, __ATOMIC_RELAXED, __HIP_MEMORY_SCOPE_AGENT); }
; #define XB_SPIN(cond, bar) do { unsigned _sp = 0; while (cond) { __builtin_amdgcn_s_sleep(1); \
;     if ((++_sp & 255u) == 0u) { if (xb_ld(&(bar)[XB_TMO])) break; if (_sp > XB_SPIN_CAP) { atomicAdd(&(bar)[XB_TMO], 1u); break; } } } } while (0)
; __device__ __forceinline__ void xcd_barrier(const XcdBarrier& b, int tid) {
;     ...
;         const unsigned old = xb_add(&bar[XB_XSUB(b.x)], 1u);
;         const unsigned gen = old / nloc;
;         if (old + 1u == (gen + 1u) * nloc) {
;             __builtin_amdgcn_fence(__ATOMIC_RELEASE, "agent");
;             asm volatile("s_waitcnt vmcnt(0)" ::: "memory");
;             const unsigned og = xb_add(&bar[XB_TOP], 1u);
;             const unsigned tg = og / nx;
;             if (og + 1u == (tg + 1u) * nx) xb_add(&bar[XB_TOPGEN], 1u);
;             else XB_SPIN(xb_ld(&bar[XB_TOPGEN]) == tg, bar);
;             __builtin_amdgcn_fence(__ATOMIC_ACQUIRE, "agent");
;             xb_add(&bar[XB_XGEN(b.x)], 1u);
;             asm volatile("s_waitcnt vmcnt(0)" ::: "memory");
;         } else {
;             XB_SPIN(xb_ld(&bar[XB_XGEN(b.x)]) == gen, bar);
.LBB0_378:
	s_or_b64 exec, exec, s[10:11]
	v_cvt_f32_u32_e32 v5, v3
	s_waitcnt vmcnt(0)
	buffer_inv sc1
	v_readfirstlane_b32 s3, v4
	v_sub_u32_e32 v4, 0, v3
	v_rcp_iflag_f32_e32 v5, v5
	v_add_u32_e32 v6, s3, v2
	v_mul_f32_e32 v5, 0x4f7ffffe, v5
	v_cvt_u32_f32_e32 v5, v5
	v_mul_lo_u32 v2, v4, v5
	v_mul_hi_u32 v2, v5, v2
	v_add_u32_e32 v2, v5, v2
	v_mul_hi_u32 v2, v6, v2
	v_mul_lo_u32 v4, v2, v3
	v_sub_u32_e32 v4, v6, v4
	v_add_u32_e32 v5, 1, v2
	v_cmp_ge_u32_e32 vcc, v4, v3
	s_nop 1
	v_cndmask_b32_e32 v2, v2, v5, vcc
	v_sub_u32_e32 v5, v4, v3
	v_cndmask_b32_e32 v4, v4, v5, vcc
	v_add_u32_e32 v5, 1, v2
	v_cmp_ge_u32_e32 vcc, v4, v3
	v_add_u32_e32 v4, 1, v6
	s_nop 0
	v_cndmask_b32_e32 v2, v2, v5, vcc
	v_mul_lo_u32 v5, v3, v2
	v_add_u32_e32 v3, v5, v3
	v_cmp_ne_u32_e32 vcc, v4, v3
	s_and_saveexec_b64 s[8:9], vcc
	s_xor_b64 s[8:9], exec, s[8:9]
	s_cbranch_execz .LBB0_392
	s_waitcnt lgkmcnt(0)
	v_add_u32_e32 v7, 1, v2
	v_mul_lo_u32 v7, v7, v1
	v_mov_b32_e32 v1, 0x3000
	global_load_dword v1, v1, s[4:5] offset:1024 sc1
	s_add_u32 s12, s4, 0x3400
	s_addc_u32 s13, s5, 0
	s_waitcnt vmcnt(0)
	v_cmp_lt_u32_e32 vcc, v1, v7
	s_and_saveexec_b64 s[10:11], vcc
	s_cbranch_execz .LBB0_391
	s_mov_b32 s3, 1
	s_mov_b64 s[14:15], 0
	v_mov_b32_e32 v1, 0
	s_branch .LBB0_382

; __device__ __forceinline__ unsigned xb_ld(unsigned* p)              { return __hip_atomic_load(p, __ATOMIC_RELAXED, __HIP_MEMORY_SCOPE_AGENT); }
; #define XB_SPIN(cond, bar) do { unsigned _sp = 0; while (cond) { __builtin_amdgcn_s_sleep(1); \
;     if ((++_sp & 255u) == 0u) { if (xb_ld(&(bar)[XB_TMO])) break; if (_sp > XB_SPIN_CAP) { atomicAdd(&(bar)[XB_TMO], 1u); break; } } } } while (0)
; __device__ __forceinline__ void xcd_barrier(const XcdBarrier& b, int tid) {
;     ...
;             XB_SPIN(xb_ld(&bar[XB_XGEN(b.x)]) == gen, bar);
.LBB0_384:
	global_load_dword v3, v1, s[12:13] sc1
	s_add_i32 s3, s3, 1
	s_mov_b64 s[20:21], -1
	s_waitcnt vmcnt(0)
	v_cmp_ge_u32_e32 vcc, v3, v7
	s_orn2_b64 s[18:19], vcc, exec
	s_branch .LBB0_381

; __device__ __forceinline__ unsigned xb_ld(unsigned* p)              { return __hip_atomic_load(p, __ATOMIC_RELAXED, __HIP_MEMORY_SCOPE_AGENT); }
; __device__ __forceinline__ unsigned xb_add(unsigned* p, unsigned v) { return __hip_atomic_fetch_add(p, v, __ATOMIC_RELAXED, __HIP_MEMORY_SCOPE_AGENT); }
; #define XB_SPIN(cond, bar) do { unsigned _sp = 0; while (cond) { __builtin_amdgcn_s_sleep(1); \
;     if ((++_sp & 255u) == 0u) { if (xb_ld(&(bar)[XB_TMO])) break; if (_sp > XB_SPIN_CAP) { atomicAdd(&(bar)[XB_TMO], 1u); break; } } } } while (0)
; __device__ __forceinline__ void xcd_barrier(const XcdBarrier& b, int tid) {
;     ...
;         if (old + 1u == (gen + 1u) * nloc) {
;             __builtin_amdgcn_fence(__ATOMIC_RELEASE, "agent");
;             asm volatile("s_waitcnt vmcnt(0)" ::: "memory");
;             const unsigned og = xb_add(&bar[XB_TOP], 1u);
;             const unsigned tg = og / nx;
;             if (og + 1u == (tg + 1u) * nx) xb_add(&bar[XB_TOPGEN], 1u);
;             else XB_SPIN(xb_ld(&bar[XB_TOPGEN]) == tg, bar);
.LBB0_395:
	s_or_b64 exec, exec, s[10:11]
	v_cvt_f32_u32_e32 v4, v1
	s_waitcnt vmcnt(0)
	v_readfirstlane_b32 s3, v3
	s_add_u32 s10, s4, 0x3400
	s_addc_u32 s11, s5, 0
	v_rcp_iflag_f32_e32 v4, v4
	v_add_u32_e32 v2, s3, v2
	v_add_u32_e32 v5, 1, v2
	s_mov_b64 s[12:13], -1
	v_mul_f32_e32 v3, 0x4f7ffffe, v4
	v_cvt_u32_f32_e32 v3, v3
	v_sub_u32_e32 v4, 0, v1
	v_mul_lo_u32 v4, v4, v3
	v_mul_hi_u32 v4, v3, v4
	v_add_u32_e32 v3, v3, v4
	v_mul_hi_u32 v3, v2, v3
	v_mul_lo_u32 v4, v3, v1
	v_sub_u32_e32 v2, v2, v4
	v_add_u32_e32 v6, 1, v3
	v_cmp_ge_u32_e32 vcc, v2, v1
	v_sub_u32_e32 v4, v2, v1
	s_nop 0
	v_cndmask_b32_e32 v3, v3, v6, vcc
	v_cndmask_b32_e32 v2, v2, v4, vcc
	v_add_u32_e32 v4, 1, v3
	v_cmp_ge_u32_e32 vcc, v2, v1
	s_nop 1
	v_cndmask_b32_e32 v4, v3, v4, vcc
	v_mul_lo_u32 v2, v1, v4
	v_add_u32_e32 v1, v2, v1
	v_mov_b32_e32 v7, v1
	v_cmp_ne_u32_e32 vcc, v5, v1
	v_mov_b64_e32 v[2:3], s[10:11]
	s_and_saveexec_b64 s[8:9], vcc
	s_cbranch_execz .LBB0_407
	v_mov_b32_e32 v1, 0
	global_load_dword v2, v1, s[10:11] sc1
	s_mov_b64 s[16:17], 0
	s_waitcnt vmcnt(0)
	v_cmp_lt_u32_e32 vcc, v2, v7
	s_and_saveexec_b64 s[14:15], vcc
	s_cbranch_execz .LBB0_406
	s_add_u32 s12, s4, 0x200
	s_addc_u32 s13, s5, 0
	s_mov_b32 s3, 1
	s_mov_b64 s[4:5], 0
	s_branch .LBB0_399

; __device__ __forceinline__ unsigned xb_ld(unsigned* p)              { return __hip_atomic_load(p, __ATOMIC_RELAXED, __HIP_MEMORY_SCOPE_AGENT); }
; #define XB_SPIN(cond, bar) do { unsigned _sp = 0; while (cond) { __builtin_amdgcn_s_sleep(1); \
;     if ((++_sp & 255u) == 0u) { if (xb_ld(&(bar)[XB_TMO])) break; if (_sp > XB_SPIN_CAP) { atomicAdd(&(bar)[XB_TMO], 1u); break; } } } } while (0)
; __device__ __forceinline__ void xcd_barrier(const XcdBarrier& b, int tid) {
;     ...
;             else XB_SPIN(xb_ld(&bar[XB_TOPGEN]) == tg, bar);
.LBB0_401:
	global_load_dword v2, v1, s[10:11] sc1
	s_add_i32 s3, s3, 1
	s_mov_b64 s[18:19], -1
	s_waitcnt vmcnt(0)
	v_cmp_ge_u32_e32 vcc, v2, v7
	s_orn2_b64 s[22:23], vcc, exec
	s_branch .LBB0_398

; __device__ __forceinline__ unsigned xb_ld(unsigned* p)              { return __hip_atomic_load(p, __ATOMIC_RELAXED, __HIP_MEMORY_SCOPE_AGENT); }
; __device__ __forceinline__ unsigned xb_add(unsigned* p, unsigned v) { return __hip_atomic_fetch_add(p, v, __ATOMIC_RELAXED, __HIP_MEMORY_SCOPE_AGENT); }
; #define XB_SPIN(cond, bar) do { unsigned _sp = 0; while (cond) { __builtin_amdgcn_s_sleep(1); \
;     if ((++_sp & 255u) == 0u) { if (xb_ld(&(bar)[XB_TMO])) break; if (_sp > XB_SPIN_CAP) { atomicAdd(&(bar)[XB_TMO], 1u); break; } } } } while (0)
; __device__ __forceinline__ void xcd_barrier(const XcdBarrier& b, int tid) {
;     ...
;             if (og + 1u == (tg + 1u) * nx) xb_add(&bar[XB_TOPGEN], 1u);
;             else XB_SPIN(xb_ld(&bar[XB_TOPGEN]) == tg, bar);
;             __builtin_amdgcn_fence(__ATOMIC_ACQUIRE, "agent");
;             xb_add(&bar[XB_XGEN(b.x)], 1u);
;             asm volatile("s_waitcnt vmcnt(0)" ::: "memory");
.LBB0_407:
	s_or_b64 exec, exec, s[8:9]
	s_and_saveexec_b64 s[4:5], s[12:13]
	s_cbranch_execz .LBB0_409
	v_mov_b32_e32 v1, 1
.LBB0_409:
	s_or_b64 exec, exec, s[4:5]
	s_mov_b64 s[4:5], exec
	v_mbcnt_lo_u32_b32 v1, s4, 0
	v_mbcnt_hi_u32_b32 v1, s5, v1
	v_cmp_eq_u32_e32 vcc, 0, v1
	s_waitcnt vmcnt(0)
	s_and_saveexec_b64 s[8:9], vcc
	s_cbranch_execz .LBB0_411
	s_bcnt1_i32_b64 s3, s[4:5]
	v_mov_b32_e32 v1, 0x2000
	v_mov_b32_e32 v2, s3

; __device__ __forceinline__ unsigned xb_ld(unsigned* p)              { return __hip_atomic_load(p, __ATOMIC_RELAXED, __HIP_MEMORY_SCOPE_AGENT); }
; __device__ __forceinline__ unsigned xb_add(unsigned* p, unsigned v) { return __hip_atomic_fetch_add(p, v, __ATOMIC_RELAXED, __HIP_MEMORY_SCOPE_AGENT); }
; #define XB_SPIN(cond, bar) do { unsigned _sp = 0; while (cond) { __builtin_amdgcn_s_sleep(1); \
;     if ((++_sp & 255u) == 0u) { if (xb_ld(&(bar)[XB_TMO])) break; if (_sp > XB_SPIN_CAP) { atomicAdd(&(bar)[XB_TMO], 1u); break; } } } } while (0)
; __device__ __forceinline__ void xcd_barrier(const XcdBarrier& b, int tid) {
;     ...
;             if (og + 1u == (tg + 1u) * nx) xb_add(&bar[XB_TOPGEN], 1u);
;             else XB_SPIN(xb_ld(&bar[XB_TOPGEN]) == tg, bar);
;             __builtin_amdgcn_fence(__ATOMIC_ACQUIRE, "agent");
;             xb_add(&bar[XB_XGEN(b.x)], 1u);
;             asm volatile("s_waitcnt vmcnt(0)" ::: "memory");
.LBB0_521:
	s_or_b64 exec, exec, s[8:9]
	s_and_saveexec_b64 s[4:5], s[12:13]
	s_cbranch_execz .LBB0_523
	v_mov_b32_e32 v1, 1
.LBB0_523:
	s_or_b64 exec, exec, s[4:5]
	s_mov_b64 s[4:5], exec
	v_mbcnt_lo_u32_b32 v1, s4, 0
	v_mbcnt_hi_u32_b32 v1, s5, v1
	v_cmp_eq_u32_e32 vcc, 0, v1
	s_waitcnt vmcnt(0)
	s_and_saveexec_b64 s[8:9], vcc
	s_cbranch_execz .LBB0_525
	s_bcnt1_i32_b64 s3, s[4:5]
	v_mov_b32_e32 v1, 0x2000
	v_mov_b32_e32 v2, s3

; __device__ __forceinline__ unsigned xb_ld(unsigned* p)              { return __hip_atomic_load(p, __ATOMIC_RELAXED, __HIP_MEMORY_SCOPE_AGENT); }
; __device__ __forceinline__ unsigned xb_add(unsigned* p, unsigned v) { return __hip_atomic_fetch_add(p, v, __ATOMIC_RELAXED, __HIP_MEMORY_SCOPE_AGENT); }
; #define XB_SPIN(cond, bar) do { unsigned _sp = 0; while (cond) { __builtin_amdgcn_s_sleep(1); \
;     if ((++_sp & 255u) == 0u) { if (xb_ld(&(bar)[XB_TMO])) break; if (_sp > XB_SPIN_CAP) { atomicAdd(&(bar)[XB_TMO], 1u); break; } } } } while (0)
; __device__ __forceinline__ void xcd_barrier(const XcdBarrier& b, int tid) {
;     ...
;             if (og + 1u == (tg + 1u) * nx) xb_add(&bar[XB_TOPGEN], 1u);
;             else XB_SPIN(xb_ld(&bar[XB_TOPGEN]) == tg, bar);
;             __builtin_amdgcn_fence(__ATOMIC_ACQUIRE, "agent");
;             xb_add(&bar[XB_XGEN(b.x)], 1u);
;             asm volatile("s_waitcnt vmcnt(0)" ::: "memory");
.LBB0_631:
	s_or_b64 exec, exec, s[8:9]
	s_and_saveexec_b64 s[4:5], s[12:13]
	s_cbranch_execz .LBB0_633
	v_mov_b32_e32 v1, 1
.LBB0_633:
	s_or_b64 exec, exec, s[4:5]
	s_mov_b64 s[4:5], exec
	v_mbcnt_lo_u32_b32 v1, s4, 0
	v_mbcnt_hi_u32_b32 v1, s5, v1
	v_cmp_eq_u32_e32 vcc, 0, v1
	s_waitcnt vmcnt(0)
	s_and_saveexec_b64 s[8:9], vcc
	s_cbranch_execz .LBB0_635
	s_bcnt1_i32_b64 s3, s[4:5]
	v_mov_b32_e32 v1, 0x2000
	v_mov_b32_e32 v2, s3

; __device__ __forceinline__ unsigned xb_ld(unsigned* p)              { return __hip_atomic_load(p, __ATOMIC_RELAXED, __HIP_MEMORY_SCOPE_AGENT); }
; __device__ __forceinline__ unsigned xb_add(unsigned* p, unsigned v) { return __hip_atomic_fetch_add(p, v, __ATOMIC_RELAXED, __HIP_MEMORY_SCOPE_AGENT); }
; #define XB_SPIN(cond, bar) do { unsigned _sp = 0; while (cond) { __builtin_amdgcn_s_sleep(1); \
;     if ((++_sp & 255u) == 0u) { if (xb_ld(&(bar)[XB_TMO])) break; if (_sp > XB_SPIN_CAP) { atomicAdd(&(bar)[XB_TMO], 1u); break; } } } } while (0)
; __device__ __forceinline__ void xcd_barrier(const XcdBarrier& b, int tid) {
;     ...
;             if (og + 1u == (tg + 1u) * nx) xb_add(&bar[XB_TOPGEN], 1u);
;             else XB_SPIN(xb_ld(&bar[XB_TOPGEN]) == tg, bar);
;             __builtin_amdgcn_fence(__ATOMIC_ACQUIRE, "agent");
;             xb_add(&bar[XB_XGEN(b.x)], 1u);
;             asm volatile("s_waitcnt vmcnt(0)" ::: "memory");
.LBB0_1358:
	s_or_b64 exec, exec, s[8:9]
	s_and_saveexec_b64 s[4:5], s[12:13]
	s_cbranch_execz .LBB0_1360
	v_mov_b32_e32 v1, 1
.LBB0_1360:
	s_or_b64 exec, exec, s[4:5]
	s_mov_b64 s[4:5], exec
	v_mbcnt_lo_u32_b32 v1, s4, 0
	v_mbcnt_hi_u32_b32 v1, s5, v1
	v_cmp_eq_u32_e32 vcc, 0, v1
	s_waitcnt vmcnt(0)
	s_and_saveexec_b64 s[8:9], vcc
	s_cbranch_execz .LBB0_1362
	s_bcnt1_i32_b64 s3, s[4:5]
	v_mov_b32_e32 v1, 0x2000
	v_mov_b32_e32 v2, s3

; __device__ __forceinline__ unsigned xb_ld(unsigned* p)              { return __hip_atomic_load(p, __ATOMIC_RELAXED, __HIP_MEMORY_SCOPE_AGENT); }
; __device__ __forceinline__ unsigned xb_add(unsigned* p, unsigned v) { return __hip_atomic_fetch_add(p, v, __ATOMIC_RELAXED, __HIP_MEMORY_SCOPE_AGENT); }
; #define XB_SPIN(cond, bar) do { unsigned _sp = 0; while (cond) { __builtin_amdgcn_s_sleep(1); \
;     if ((++_sp & 255u) == 0u) { if (xb_ld(&(bar)[XB_TMO])) break; if (_sp > XB_SPIN_CAP) { atomicAdd(&(bar)[XB_TMO], 1u); break; } } } } while (0)
; __device__ __forceinline__ void xcd_barrier(const XcdBarrier& b, int tid) {
;     ...
;             if (og + 1u == (tg + 1u) * nx) xb_add(&bar[XB_TOPGEN], 1u);
;             else XB_SPIN(xb_ld(&bar[XB_TOPGEN]) == tg, bar);
;             __builtin_amdgcn_fence(__ATOMIC_ACQUIRE, "agent");
;             xb_add(&bar[XB_XGEN(b.x)], 1u);
;             asm volatile("s_waitcnt vmcnt(0)" ::: "memory");
.LBB0_1568:
	s_or_b64 exec, exec, s[10:11]
	s_and_saveexec_b64 s[6:7], s[14:15]
	s_cbranch_execz .LBB0_1570
	v_mov_b32_e32 v1, 1
.LBB0_1570:
	s_or_b64 exec, exec, s[6:7]
	s_mov_b64 s[6:7], exec
	v_mbcnt_lo_u32_b32 v1, s6, 0
	v_mbcnt_hi_u32_b32 v1, s7, v1
	v_cmp_eq_u32_e32 vcc, 0, v1
	s_waitcnt vmcnt(0)
	s_and_saveexec_b64 s[10:11], vcc
	s_cbranch_execz .LBB0_1572
	s_bcnt1_i32_b64 s3, s[6:7]
	v_mov_b32_e32 v1, 0x2000
	v_mov_b32_e32 v2, s3

; __device__ __forceinline__ unsigned xb_ld(unsigned* p)              { return __hip_atomic_load(p, __ATOMIC_RELAXED, __HIP_MEMORY_SCOPE_AGENT); }
; __device__ __forceinline__ unsigned xb_add(unsigned* p, unsigned v) { return __hip_atomic_fetch_add(p, v, __ATOMIC_RELAXED, __HIP_MEMORY_SCOPE_AGENT); }
; #define XB_SPIN(cond, bar) do { unsigned _sp = 0; while (cond) { __builtin_amdgcn_s_sleep(1); \
;     if ((++_sp & 255u) == 0u) { if (xb_ld(&(bar)[XB_TMO])) break; if (_sp > XB_SPIN_CAP) { atomicAdd(&(bar)[XB_TMO], 1u); break; } } } } while (0)
; __device__ __forceinline__ void xcd_barrier(const XcdBarrier& b, int tid) {
;     ...
;             if (og + 1u == (tg + 1u) * nx) xb_add(&bar[XB_TOPGEN], 1u);
;             else XB_SPIN(xb_ld(&bar[XB_TOPGEN]) == tg, bar);
;             __builtin_amdgcn_fence(__ATOMIC_ACQUIRE, "agent");
;             xb_add(&bar[XB_XGEN(b.x)], 1u);
;             asm volatile("s_waitcnt vmcnt(0)" ::: "memory");
.LBB0_1802:
	s_or_b64 exec, exec, s[10:11]
	s_and_saveexec_b64 s[6:7], s[14:15]
	s_cbranch_execz .LBB0_1804
	v_mov_b32_e32 v1, 1
.LBB0_1804:
	s_or_b64 exec, exec, s[6:7]
	s_mov_b64 s[6:7], exec
	v_mbcnt_lo_u32_b32 v1, s6, 0
	v_mbcnt_hi_u32_b32 v1, s7, v1
	v_cmp_eq_u32_e32 vcc, 0, v1
	s_waitcnt vmcnt(0)
	s_and_saveexec_b64 s[10:11], vcc
	s_cbranch_execz .LBB0_1806
	s_bcnt1_i32_b64 s3, s[6:7]
	v_mov_b32_e32 v1, 0x2000
	v_mov_b32_e32 v2, s3

; __device__ __forceinline__ unsigned xb_ld(unsigned* p)              { return __hip_atomic_load(p, __ATOMIC_RELAXED, __HIP_MEMORY_SCOPE_AGENT); }
; __device__ __forceinline__ unsigned xb_add(unsigned* p, unsigned v) { return __hip_atomic_fetch_add(p, v, __ATOMIC_RELAXED, __HIP_MEMORY_SCOPE_AGENT); }
; #define XB_SPIN(cond, bar) do { unsigned _sp = 0; while (cond) { __builtin_amdgcn_s_sleep(1); \
;     if ((++_sp & 255u) == 0u) { if (xb_ld(&(bar)[XB_TMO])) break; if (_sp > XB_SPIN_CAP) { atomicAdd(&(bar)[XB_TMO], 1u); break; } } } } while (0)
; __device__ __forceinline__ void xcd_barrier(const XcdBarrier& b, int tid) {
;     ...
;             if (og + 1u == (tg + 1u) * nx) xb_add(&bar[XB_TOPGEN], 1u);
;             else XB_SPIN(xb_ld(&bar[XB_TOPGEN]) == tg, bar);
;             __builtin_amdgcn_fence(__ATOMIC_ACQUIRE, "agent");
;             xb_add(&bar[XB_XGEN(b.x)], 1u);
;             asm volatile("s_waitcnt vmcnt(0)" ::: "memory");
.LBB0_1978:
	s_or_b64 exec, exec, s[10:11]
	s_and_saveexec_b64 s[6:7], s[14:15]
	s_cbranch_execz .LBB0_1980
	v_mov_b32_e32 v1, 1
.LBB0_1980:
	s_or_b64 exec, exec, s[6:7]
	s_mov_b64 s[6:7], exec
	v_mbcnt_lo_u32_b32 v1, s6, 0
	v_mbcnt_hi_u32_b32 v1, s7, v1
	v_cmp_eq_u32_e32 vcc, 0, v1
	s_waitcnt vmcnt(0)
	s_and_saveexec_b64 s[10:11], vcc
	s_cbranch_execz .LBB0_1982
	s_bcnt1_i32_b64 s3, s[6:7]
	v_mov_b32_e32 v1, 0x2000
	v_mov_b32_e32 v2, s3

; __device__ __forceinline__ unsigned xb_ld(unsigned* p)              { return __hip_atomic_load(p, __ATOMIC_RELAXED, __HIP_MEMORY_SCOPE_AGENT); }
; __device__ __forceinline__ unsigned xb_add(unsigned* p, unsigned v) { return __hip_atomic_fetch_add(p, v, __ATOMIC_RELAXED, __HIP_MEMORY_SCOPE_AGENT); }
; #define XB_SPIN(cond, bar) do { unsigned _sp = 0; while (cond) { __builtin_amdgcn_s_sleep(1); \
;     if ((++_sp & 255u) == 0u) { if (xb_ld(&(bar)[XB_TMO])) break; if (_sp > XB_SPIN_CAP) { atomicAdd(&(bar)[XB_TMO], 1u); break; } } } } while (0)
; __device__ __forceinline__ void xcd_barrier(const XcdBarrier& b, int tid) {
;     ...
;             if (og + 1u == (tg + 1u) * nx) xb_add(&bar[XB_TOPGEN], 1u);
;             else XB_SPIN(xb_ld(&bar[XB_TOPGEN]) == tg, bar);
;             __builtin_amdgcn_fence(__ATOMIC_ACQUIRE, "agent");
;             xb_add(&bar[XB_XGEN(b.x)], 1u);
;             asm volatile("s_waitcnt vmcnt(0)" ::: "memory");
.LBB0_2102:
	s_or_b64 exec, exec, s[8:9]
	s_and_saveexec_b64 s[4:5], s[12:13]
	s_cbranch_execz .LBB0_2104
	v_mov_b32_e32 v1, 1
.LBB0_2104:
	s_or_b64 exec, exec, s[4:5]
	s_mov_b64 s[4:5], exec
	v_mbcnt_lo_u32_b32 v1, s4, 0
	v_mbcnt_hi_u32_b32 v1, s5, v1
	v_cmp_eq_u32_e32 vcc, 0, v1
	s_waitcnt vmcnt(0)
	s_and_saveexec_b64 s[8:9], vcc
	s_cbranch_execz .LBB0_2106
	s_bcnt1_i32_b64 s3, s[4:5]
	v_mov_b32_e32 v1, 0x2000
	v_mov_b32_e32 v2, s3

; __device__ __forceinline__ unsigned xb_ld(unsigned* p)              { return __hip_atomic_load(p, __ATOMIC_RELAXED, __HIP_MEMORY_SCOPE_AGENT); }
; __device__ __forceinline__ unsigned xb_add(unsigned* p, unsigned v) { return __hip_atomic_fetch_add(p, v, __ATOMIC_RELAXED, __HIP_MEMORY_SCOPE_AGENT); }
; #define XB_SPIN(cond, bar) do { unsigned _sp = 0; while (cond) { __builtin_amdgcn_s_sleep(1); \
;     if ((++_sp & 255u) == 0u) { if (xb_ld(&(bar)[XB_TMO])) break; if (_sp > XB_SPIN_CAP) { atomicAdd(&(bar)[XB_TMO], 1u); break; } } } } while (0)
; __device__ __forceinline__ void xcd_barrier(const XcdBarrier& b, int tid) {
;     ...
;             if (og + 1u == (tg + 1u) * nx) xb_add(&bar[XB_TOPGEN], 1u);
;             else XB_SPIN(xb_ld(&bar[XB_TOPGEN]) == tg, bar);
;             __builtin_amdgcn_fence(__ATOMIC_ACQUIRE, "agent");
;             xb_add(&bar[XB_XGEN(b.x)], 1u);
;             asm volatile("s_waitcnt vmcnt(0)" ::: "memory");
.LBB0_2208:
	s_or_b64 exec, exec, s[8:9]
	s_and_saveexec_b64 s[4:5], s[12:13]
	s_cbranch_execz .LBB0_2210
	v_mov_b32_e32 v1, 1
.LBB0_2210:
	s_or_b64 exec, exec, s[4:5]
	s_mov_b64 s[4:5], exec
	v_mbcnt_lo_u32_b32 v1, s4, 0
	v_mbcnt_hi_u32_b32 v1, s5, v1
	v_cmp_eq_u32_e32 vcc, 0, v1
	s_waitcnt vmcnt(0)
	s_and_saveexec_b64 s[8:9], vcc
	s_cbranch_execz .LBB0_2212
	s_bcnt1_i32_b64 s3, s[4:5]
	v_mov_b32_e32 v1, 0x2000
	v_mov_b32_e32 v2, s3

; __device__ __forceinline__ unsigned xb_ld(unsigned* p)              { return __hip_atomic_load(p, __ATOMIC_RELAXED, __HIP_MEMORY_SCOPE_AGENT); }
; __device__ __forceinline__ unsigned xb_add(unsigned* p, unsigned v) { return __hip_atomic_fetch_add(p, v, __ATOMIC_RELAXED, __HIP_MEMORY_SCOPE_AGENT); }
; #define XB_SPIN(cond, bar) do { unsigned _sp = 0; while (cond) { __builtin_amdgcn_s_sleep(1); \
;     if ((++_sp & 255u) == 0u) { if (xb_ld(&(bar)[XB_TMO])) break; if (_sp > XB_SPIN_CAP) { atomicAdd(&(bar)[XB_TMO], 1u); break; } } } } while (0)
; __device__ __forceinline__ void xcd_barrier(const XcdBarrier& b, int tid) {
;     ...
;             if (og + 1u == (tg + 1u) * nx) xb_add(&bar[XB_TOPGEN], 1u);
;             else XB_SPIN(xb_ld(&bar[XB_TOPGEN]) == tg, bar);
;             __builtin_amdgcn_fence(__ATOMIC_ACQUIRE, "agent");
;             xb_add(&bar[XB_XGEN(b.x)], 1u);
;             asm volatile("s_waitcnt vmcnt(0)" ::: "memory");
.LBB0_2322:
	s_or_b64 exec, exec, s[8:9]
	s_and_saveexec_b64 s[4:5], s[12:13]
	s_cbranch_execz .LBB0_2324
	v_mov_b32_e32 v1, 1
.LBB0_2324:
	s_or_b64 exec, exec, s[4:5]
	s_mov_b64 s[4:5], exec
	v_mbcnt_lo_u32_b32 v1, s4, 0
	v_mbcnt_hi_u32_b32 v1, s5, v1
	v_cmp_eq_u32_e32 vcc, 0, v1
	s_waitcnt vmcnt(0)
	s_and_saveexec_b64 s[8:9], vcc
	s_cbranch_execz .LBB0_2326
	s_bcnt1_i32_b64 s3, s[4:5]
	v_mov_b32_e32 v1, 0x2000
	v_mov_b32_e32 v2, s3

; __device__ __forceinline__ unsigned xb_ld(unsigned* p)              { return __hip_atomic_load(p, __ATOMIC_RELAXED, __HIP_MEMORY_SCOPE_AGENT); }
; __device__ __forceinline__ unsigned xb_add(unsigned* p, unsigned v) { return __hip_atomic_fetch_add(p, v, __ATOMIC_RELAXED, __HIP_MEMORY_SCOPE_AGENT); }
; #define XB_SPIN(cond, bar) do { unsigned _sp = 0; while (cond) { __builtin_amdgcn_s_sleep(1); \
;     if ((++_sp & 255u) == 0u) { if (xb_ld(&(bar)[XB_TMO])) break; if (_sp > XB_SPIN_CAP) { atomicAdd(&(bar)[XB_TMO], 1u); break; } } } } while (0)
; __device__ __forceinline__ void xcd_barrier(const XcdBarrier& b, int tid) {
;     ...
;             if (og + 1u == (tg + 1u) * nx) xb_add(&bar[XB_TOPGEN], 1u);
;             else XB_SPIN(xb_ld(&bar[XB_TOPGEN]) == tg, bar);
;             __builtin_amdgcn_fence(__ATOMIC_ACQUIRE, "agent");
;             xb_add(&bar[XB_XGEN(b.x)], 1u);
;             asm volatile("s_waitcnt vmcnt(0)" ::: "memory");
.LBB0_2432:
	s_or_b64 exec, exec, s[8:9]
	s_and_saveexec_b64 s[4:5], s[12:13]
	s_cbranch_execz .LBB0_2434
	v_mov_b32_e32 v1, 1
.LBB0_2434:
	s_or_b64 exec, exec, s[4:5]
	s_mov_b64 s[4:5], exec
	v_mbcnt_lo_u32_b32 v1, s4, 0
	v_mbcnt_hi_u32_b32 v1, s5, v1
	v_cmp_eq_u32_e32 vcc, 0, v1
	s_waitcnt vmcnt(0)
	s_and_saveexec_b64 s[8:9], vcc
	s_cbranch_execz .LBB0_2436
	s_bcnt1_i32_b64 s3, s[4:5]
	v_mov_b32_e32 v1, 0x2000
	v_mov_b32_e32 v2, s3

; __device__ __forceinline__ unsigned xb_ld(unsigned* p)              { return __hip_atomic_load(p, __ATOMIC_RELAXED, __HIP_MEMORY_SCOPE_AGENT); }
; __device__ __forceinline__ unsigned xb_add(unsigned* p, unsigned v) { return __hip_atomic_fetch_add(p, v, __ATOMIC_RELAXED, __HIP_MEMORY_SCOPE_AGENT); }
; #define XB_SPIN(cond, bar) do { unsigned _sp = 0; while (cond) { __builtin_amdgcn_s_sleep(1); \
;     if ((++_sp & 255u) == 0u) { if (xb_ld(&(bar)[XB_TMO])) break; if (_sp > XB_SPIN_CAP) { atomicAdd(&(bar)[XB_TMO], 1u); break; } } } } while (0)
; __device__ __forceinline__ void xcd_barrier(const XcdBarrier& b, int tid) {
;     ...
;             if (og + 1u == (tg + 1u) * nx) xb_add(&bar[XB_TOPGEN], 1u);
;             else XB_SPIN(xb_ld(&bar[XB_TOPGEN]) == tg, bar);
;             __builtin_amdgcn_fence(__ATOMIC_ACQUIRE, "agent");
;             xb_add(&bar[XB_XGEN(b.x)], 1u);
;             asm volatile("s_waitcnt vmcnt(0)" ::: "memory");
.LBB0_2546:
	s_or_b64 exec, exec, s[8:9]
	s_and_saveexec_b64 s[4:5], s[12:13]
	s_cbranch_execz .LBB0_2548
	v_mov_b32_e32 v1, 1
.LBB0_2548:
	s_or_b64 exec, exec, s[4:5]
	s_mov_b64 s[4:5], exec
	v_mbcnt_lo_u32_b32 v1, s4, 0
	v_mbcnt_hi_u32_b32 v1, s5, v1
	v_cmp_eq_u32_e32 vcc, 0, v1
	s_waitcnt vmcnt(0)
	s_and_saveexec_b64 s[8:9], vcc
	s_cbranch_execz .LBB0_2550
	s_bcnt1_i32_b64 s3, s[4:5]
	v_mov_b32_e32 v1, 0x2000
	v_mov_b32_e32 v2, s3

; __device__ __forceinline__ unsigned xb_ld(unsigned* p)              { return __hip_atomic_load(p, __ATOMIC_RELAXED, __HIP_MEMORY_SCOPE_AGENT); }
; __device__ __forceinline__ unsigned xb_add(unsigned* p, unsigned v) { return __hip_atomic_fetch_add(p, v, __ATOMIC_RELAXED, __HIP_MEMORY_SCOPE_AGENT); }
; #define XB_SPIN(cond, bar) do { unsigned _sp = 0; while (cond) { __builtin_amdgcn_s_sleep(1); \
;     if ((++_sp & 255u) == 0u) { if (xb_ld(&(bar)[XB_TMO])) break; if (_sp > XB_SPIN_CAP) { atomicAdd(&(bar)[XB_TMO], 1u); break; } } } } while (0)
; __device__ __forceinline__ void xcd_barrier(const XcdBarrier& b, int tid) {
;     ...
;             if (og + 1u == (tg + 1u) * nx) xb_add(&bar[XB_TOPGEN], 1u);
;             else XB_SPIN(xb_ld(&bar[XB_TOPGEN]) == tg, bar);
;             __builtin_amdgcn_fence(__ATOMIC_ACQUIRE, "agent");
;             xb_add(&bar[XB_XGEN(b.x)], 1u);
;             asm volatile("s_waitcnt vmcnt(0)" ::: "memory");
.LBB0_2656:
	s_or_b64 exec, exec, s[8:9]
	s_and_saveexec_b64 s[4:5], s[12:13]
	s_cbranch_execz .LBB0_2658
	v_mov_b32_e32 v1, 1
.LBB0_2658:
	s_or_b64 exec, exec, s[4:5]
	s_mov_b64 s[4:5], exec
	v_mbcnt_lo_u32_b32 v1, s4, 0
	v_mbcnt_hi_u32_b32 v1, s5, v1
	v_cmp_eq_u32_e32 vcc, 0, v1
	s_waitcnt vmcnt(0)
	s_and_saveexec_b64 s[8:9], vcc
	s_cbranch_execz .LBB0_2660
	s_bcnt1_i32_b64 s3, s[4:5]
	v_mov_b32_e32 v1, 0x2000
	v_mov_b32_e32 v2, s3

; __device__ __forceinline__ unsigned xb_ld(unsigned* p)              { return __hip_atomic_load(p, __ATOMIC_RELAXED, __HIP_MEMORY_SCOPE_AGENT); }
; __device__ __forceinline__ unsigned xb_add(unsigned* p, unsigned v) { return __hip_atomic_fetch_add(p, v, __ATOMIC_RELAXED, __HIP_MEMORY_SCOPE_AGENT); }
; #define XB_SPIN(cond, bar) do { unsigned _sp = 0; while (cond) { __builtin_amdgcn_s_sleep(1); \
;     if ((++_sp & 255u) == 0u) { if (xb_ld(&(bar)[XB_TMO])) break; if (_sp > XB_SPIN_CAP) { atomicAdd(&(bar)[XB_TMO], 1u); break; } } } } while (0)
; __device__ __forceinline__ void xcd_barrier(const XcdBarrier& b, int tid) {
;     ...
;             if (og + 1u == (tg + 1u) * nx) xb_add(&bar[XB_TOPGEN], 1u);
;             else XB_SPIN(xb_ld(&bar[XB_TOPGEN]) == tg, bar);
;             __builtin_amdgcn_fence(__ATOMIC_ACQUIRE, "agent");
;             xb_add(&bar[XB_XGEN(b.x)], 1u);
;             asm volatile("s_waitcnt vmcnt(0)" ::: "memory");
.LBB0_3383:
	s_or_b64 exec, exec, s[8:9]
	s_and_saveexec_b64 s[4:5], s[12:13]
	s_cbranch_execz .LBB0_3385
	v_mov_b32_e32 v1, 1
.LBB0_3385:
	s_or_b64 exec, exec, s[4:5]
	s_mov_b64 s[4:5], exec
	v_mbcnt_lo_u32_b32 v1, s4, 0
	v_mbcnt_hi_u32_b32 v1, s5, v1
	v_cmp_eq_u32_e32 vcc, 0, v1
	s_waitcnt vmcnt(0)
	s_and_saveexec_b64 s[8:9], vcc
	s_cbranch_execz .LBB0_3387
	s_bcnt1_i32_b64 s3, s[4:5]
	v_mov_b32_e32 v1, 0x2000
	v_mov_b32_e32 v2, s3

; __device__ __forceinline__ unsigned xb_ld(unsigned* p)              { return __hip_atomic_load(p, __ATOMIC_RELAXED, __HIP_MEMORY_SCOPE_AGENT); }
; __device__ __forceinline__ unsigned xb_add(unsigned* p, unsigned v) { return __hip_atomic_fetch_add(p, v, __ATOMIC_RELAXED, __HIP_MEMORY_SCOPE_AGENT); }
; #define XB_SPIN(cond, bar) do { unsigned _sp = 0; while (cond) { __builtin_amdgcn_s_sleep(1); \
;     if ((++_sp & 255u) == 0u) { if (xb_ld(&(bar)[XB_TMO])) break; if (_sp > XB_SPIN_CAP) { atomicAdd(&(bar)[XB_TMO], 1u); break; } } } } while (0)
; __device__ __forceinline__ void xcd_barrier(const XcdBarrier& b, int tid) {
;     ...
;             if (og + 1u == (tg + 1u) * nx) xb_add(&bar[XB_TOPGEN], 1u);
;             else XB_SPIN(xb_ld(&bar[XB_TOPGEN]) == tg, bar);
;             __builtin_amdgcn_fence(__ATOMIC_ACQUIRE, "agent");
;             xb_add(&bar[XB_XGEN(b.x)], 1u);
;             asm volatile("s_waitcnt vmcnt(0)" ::: "memory");
.LBB0_3593:
	s_or_b64 exec, exec, s[10:11]
	s_and_saveexec_b64 s[6:7], s[14:15]
	s_cbranch_execz .LBB0_3595
	v_mov_b32_e32 v1, 1
.LBB0_3595:
	s_or_b64 exec, exec, s[6:7]
	s_mov_b64 s[6:7], exec
	v_mbcnt_lo_u32_b32 v1, s6, 0
	v_mbcnt_hi_u32_b32 v1, s7, v1
	v_cmp_eq_u32_e32 vcc, 0, v1
	s_waitcnt vmcnt(0)
	s_and_saveexec_b64 s[10:11], vcc
	s_cbranch_execz .LBB0_3597
	s_bcnt1_i32_b64 s3, s[6:7]
	v_mov_b32_e32 v1, 0x2000
	v_mov_b32_e32 v2, s3

; __device__ __forceinline__ unsigned xb_ld(unsigned* p)              { return __hip_atomic_load(p, __ATOMIC_RELAXED, __HIP_MEMORY_SCOPE_AGENT); }
; __device__ __forceinline__ unsigned xb_add(unsigned* p, unsigned v) { return __hip_atomic_fetch_add(p, v, __ATOMIC_RELAXED, __HIP_MEMORY_SCOPE_AGENT); }
; #define XB_SPIN(cond, bar) do { unsigned _sp = 0; while (cond) { __builtin_amdgcn_s_sleep(1); \
;     if ((++_sp & 255u) == 0u) { if (xb_ld(&(bar)[XB_TMO])) break; if (_sp > XB_SPIN_CAP) { atomicAdd(&(bar)[XB_TMO], 1u); break; } } } } while (0)
; __device__ __forceinline__ void xcd_barrier(const XcdBarrier& b, int tid) {
;     ...
;             if (og + 1u == (tg + 1u) * nx) xb_add(&bar[XB_TOPGEN], 1u);
;             else XB_SPIN(xb_ld(&bar[XB_TOPGEN]) == tg, bar);
;             __builtin_amdgcn_fence(__ATOMIC_ACQUIRE, "agent");
;             xb_add(&bar[XB_XGEN(b.x)], 1u);
;             asm volatile("s_waitcnt vmcnt(0)" ::: "memory");
.LBB0_3826:
	s_or_b64 exec, exec, s[10:11]
	s_and_saveexec_b64 s[6:7], s[14:15]
	s_cbranch_execz .LBB0_3828
	v_mov_b32_e32 v1, 1
.LBB0_3828:
	s_or_b64 exec, exec, s[6:7]
	s_mov_b64 s[6:7], exec
	v_mbcnt_lo_u32_b32 v1, s6, 0
	v_mbcnt_hi_u32_b32 v1, s7, v1
	v_cmp_eq_u32_e32 vcc, 0, v1
	s_waitcnt vmcnt(0)
	s_and_saveexec_b64 s[10:11], vcc
	s_cbranch_execz .LBB0_3830
	s_bcnt1_i32_b64 s3, s[6:7]
	v_mov_b32_e32 v1, 0x2000
	v_mov_b32_e32 v2, s3

; __device__ __forceinline__ unsigned xb_ld(unsigned* p)              { return __hip_atomic_load(p, __ATOMIC_RELAXED, __HIP_MEMORY_SCOPE_AGENT); }
; __device__ __forceinline__ unsigned xb_add(unsigned* p, unsigned v) { return __hip_atomic_fetch_add(p, v, __ATOMIC_RELAXED, __HIP_MEMORY_SCOPE_AGENT); }
; #define XB_SPIN(cond, bar) do { unsigned _sp = 0; while (cond) { __builtin_amdgcn_s_sleep(1); \
;     if ((++_sp & 255u) == 0u) { if (xb_ld(&(bar)[XB_TMO])) break; if (_sp > XB_SPIN_CAP) { atomicAdd(&(bar)[XB_TMO], 1u); break; } } } } while (0)
; __device__ __forceinline__ void xcd_barrier(const XcdBarrier& b, int tid) {
;     ...
;             if (og + 1u == (tg + 1u) * nx) xb_add(&bar[XB_TOPGEN], 1u);
;             else XB_SPIN(xb_ld(&bar[XB_TOPGEN]) == tg, bar);
;             __builtin_amdgcn_fence(__ATOMIC_ACQUIRE, "agent");
;             xb_add(&bar[XB_XGEN(b.x)], 1u);
;             asm volatile("s_waitcnt vmcnt(0)" ::: "memory");
.LBB0_4002:
	s_or_b64 exec, exec, s[10:11]
	s_and_saveexec_b64 s[6:7], s[14:15]
	s_cbranch_execz .LBB0_4004
	v_mov_b32_e32 v1, 1
.LBB0_4004:
	s_or_b64 exec, exec, s[6:7]
	s_mov_b64 s[6:7], exec
	v_mbcnt_lo_u32_b32 v1, s6, 0
	v_mbcnt_hi_u32_b32 v1, s7, v1
	v_cmp_eq_u32_e32 vcc, 0, v1
	s_waitcnt vmcnt(0)
	s_and_saveexec_b64 s[10:11], vcc
	s_cbranch_execz .LBB0_4006
	s_bcnt1_i32_b64 s3, s[6:7]
	v_mov_b32_e32 v1, 0x2000
	v_mov_b32_e32 v2, s3

; __device__ __forceinline__ unsigned xb_ld(unsigned* p)              { return __hip_atomic_load(p, __ATOMIC_RELAXED, __HIP_MEMORY_SCOPE_AGENT); }
; __device__ __forceinline__ unsigned xb_add(unsigned* p, unsigned v) { return __hip_atomic_fetch_add(p, v, __ATOMIC_RELAXED, __HIP_MEMORY_SCOPE_AGENT); }
; #define XB_SPIN(cond, bar) do { unsigned _sp = 0; while (cond) { __builtin_amdgcn_s_sleep(1); \
;     if ((++_sp & 255u) == 0u) { if (xb_ld(&(bar)[XB_TMO])) break; if (_sp > XB_SPIN_CAP) { atomicAdd(&(bar)[XB_TMO], 1u); break; } } } } while (0)
; __device__ __forceinline__ void xcd_barrier(const XcdBarrier& b, int tid) {
;     ...
;             if (og + 1u == (tg + 1u) * nx) xb_add(&bar[XB_TOPGEN], 1u);
;             else XB_SPIN(xb_ld(&bar[XB_TOPGEN]) == tg, bar);
;             __builtin_amdgcn_fence(__ATOMIC_ACQUIRE, "agent");
;             xb_add(&bar[XB_XGEN(b.x)], 1u);
;             asm volatile("s_waitcnt vmcnt(0)" ::: "memory");
.LBB0_4126:
	s_or_b64 exec, exec, s[8:9]
	s_and_saveexec_b64 s[4:5], s[12:13]
	s_cbranch_execz .LBB0_4128
	v_mov_b32_e32 v1, 1
.LBB0_4128:
	s_or_b64 exec, exec, s[4:5]
	s_mov_b64 s[4:5], exec
	v_mbcnt_lo_u32_b32 v1, s4, 0
	v_mbcnt_hi_u32_b32 v1, s5, v1
	v_cmp_eq_u32_e32 vcc, 0, v1
	s_waitcnt vmcnt(0)
	s_and_saveexec_b64 s[8:9], vcc
	s_cbranch_execz .LBB0_4130
	s_bcnt1_i32_b64 s3, s[4:5]
	v_mov_b32_e32 v1, 0x2000
	v_mov_b32_e32 v2, s3

; __device__ __forceinline__ unsigned xb_ld(unsigned* p)              { return __hip_atomic_load(p, __ATOMIC_RELAXED, __HIP_MEMORY_SCOPE_AGENT); }
; __device__ __forceinline__ unsigned xb_add(unsigned* p, unsigned v) { return __hip_atomic_fetch_add(p, v, __ATOMIC_RELAXED, __HIP_MEMORY_SCOPE_AGENT); }
; #define XB_SPIN(cond, bar) do { unsigned _sp = 0; while (cond) { __builtin_amdgcn_s_sleep(1); \
;     if ((++_sp & 255u) == 0u) { if (xb_ld(&(bar)[XB_TMO])) break; if (_sp > XB_SPIN_CAP) { atomicAdd(&(bar)[XB_TMO], 1u); break; } } } } while (0)
; __device__ __forceinline__ void xcd_barrier(const XcdBarrier& b, int tid) {
;     ...
;             if (og + 1u == (tg + 1u) * nx) xb_add(&bar[XB_TOPGEN], 1u);
;             else XB_SPIN(xb_ld(&bar[XB_TOPGEN]) == tg, bar);
;             __builtin_amdgcn_fence(__ATOMIC_ACQUIRE, "agent");
;             xb_add(&bar[XB_XGEN(b.x)], 1u);
;             asm volatile("s_waitcnt vmcnt(0)" ::: "memory");
.LBB0_4232:
	s_or_b64 exec, exec, s[8:9]
	s_and_saveexec_b64 s[4:5], s[12:13]
	s_cbranch_execz .LBB0_4234
	v_mov_b32_e32 v1, 1
.LBB0_4234:
	s_or_b64 exec, exec, s[4:5]
	s_mov_b64 s[4:5], exec
	v_mbcnt_lo_u32_b32 v1, s4, 0
	v_mbcnt_hi_u32_b32 v1, s5, v1
	v_cmp_eq_u32_e32 vcc, 0, v1
	s_waitcnt vmcnt(0)
	s_and_saveexec_b64 s[8:9], vcc
	s_cbranch_execz .LBB0_4236
	s_bcnt1_i32_b64 s3, s[4:5]
	v_mov_b32_e32 v1, 0x2000
	v_mov_b32_e32 v2, s3

; __device__ __forceinline__ unsigned xb_ld(unsigned* p)              { return __hip_atomic_load(p, __ATOMIC_RELAXED, __HIP_MEMORY_SCOPE_AGENT); }
; __device__ __forceinline__ unsigned xb_add(unsigned* p, unsigned v) { return __hip_atomic_fetch_add(p, v, __ATOMIC_RELAXED, __HIP_MEMORY_SCOPE_AGENT); }
; #define XB_SPIN(cond, bar) do { unsigned _sp = 0; while (cond) { __builtin_amdgcn_s_sleep(1); \
;     if ((++_sp & 255u) == 0u) { if (xb_ld(&(bar)[XB_TMO])) break; if (_sp > XB_SPIN_CAP) { atomicAdd(&(bar)[XB_TMO], 1u); break; } } } } while (0)
; __device__ __forceinline__ void xcd_barrier(const XcdBarrier& b, int tid) {
;     ...
;             if (og + 1u == (tg + 1u) * nx) xb_add(&bar[XB_TOPGEN], 1u);
;             else XB_SPIN(xb_ld(&bar[XB_TOPGEN]) == tg, bar);
;             __builtin_amdgcn_fence(__ATOMIC_ACQUIRE, "agent");
;             xb_add(&bar[XB_XGEN(b.x)], 1u);
;             asm volatile("s_waitcnt vmcnt(0)" ::: "memory");
.LBB0_4346:
	s_or_b64 exec, exec, s[8:9]
	s_and_saveexec_b64 s[4:5], s[12:13]
	s_cbranch_execz .LBB0_4348
	v_mov_b32_e32 v1, 1
.LBB0_4348:
	s_or_b64 exec, exec, s[4:5]
	s_mov_b64 s[4:5], exec
	v_mbcnt_lo_u32_b32 v1, s4, 0
	v_mbcnt_hi_u32_b32 v1, s5, v1
	v_cmp_eq_u32_e32 vcc, 0, v1
	s_waitcnt vmcnt(0)
	s_and_saveexec_b64 s[8:9], vcc
	s_cbranch_execz .LBB0_4350
	s_bcnt1_i32_b64 s3, s[4:5]
	v_mov_b32_e32 v1, 0x2000
	v_mov_b32_e32 v2, s3

; __device__ __forceinline__ unsigned xb_ld(unsigned* p)              { return __hip_atomic_load(p, __ATOMIC_RELAXED, __HIP_MEMORY_SCOPE_AGENT); }
; __device__ __forceinline__ unsigned xb_add(unsigned* p, unsigned v) { return __hip_atomic_fetch_add(p, v, __ATOMIC_RELAXED, __HIP_MEMORY_SCOPE_AGENT); }
; #define XB_SPIN(cond, bar) do { unsigned _sp = 0; while (cond) { __builtin_amdgcn_s_sleep(1); \
;     if ((++_sp & 255u) == 0u) { if (xb_ld(&(bar)[XB_TMO])) break; if (_sp > XB_SPIN_CAP) { atomicAdd(&(bar)[XB_TMO], 1u); break; } } } } while (0)
; __device__ __forceinline__ void xcd_barrier(const XcdBarrier& b, int tid) {
;     ...
;             if (og + 1u == (tg + 1u) * nx) xb_add(&bar[XB_TOPGEN], 1u);
;             else XB_SPIN(xb_ld(&bar[XB_TOPGEN]) == tg, bar);
;             __builtin_amdgcn_fence(__ATOMIC_ACQUIRE, "agent");
;             xb_add(&bar[XB_XGEN(b.x)], 1u);
;             asm volatile("s_waitcnt vmcnt(0)" ::: "memory");
.LBB0_4456:
	s_or_b64 exec, exec, s[8:9]
	s_and_saveexec_b64 s[4:5], s[12:13]
	s_cbranch_execz .LBB0_4458
	v_mov_b32_e32 v1, 1
.LBB0_4458:
	s_or_b64 exec, exec, s[4:5]
	s_mov_b64 s[4:5], exec
	v_mbcnt_lo_u32_b32 v1, s4, 0
	v_mbcnt_hi_u32_b32 v1, s5, v1
	v_cmp_eq_u32_e32 vcc, 0, v1
	s_waitcnt vmcnt(0)
	s_and_saveexec_b64 s[8:9], vcc
	s_cbranch_execz .LBB0_4460
	s_bcnt1_i32_b64 s3, s[4:5]
	v_mov_b32_e32 v1, 0x2000
	v_mov_b32_e32 v2, s3
